# evod_bar2
# baseline (speedup 1.0000x reference)
; template <int EPI>
; __device__ __forceinline__ void gemm_phase(const GemmArgs& G, char* shm) {
;   const int nwg = G.nM * G.nN;
;   const int vb = vbid();
;   for (int t = vb; t < nwg; t += gridDim.x) {
;     int brow, bcol, nbrow = 0, nbcol = 0; gemm_map_tile(G, t, brow, bcol);
;     const bool has_next = t + (int)gridDim.x < nwg;
;     if (has_next) gemm_map_tile(G, t + gridDim.x, nbrow, nbcol);
;     gemm_tile<EPI>(G, brow, bcol, shm, t == vb, has_next, nbrow, nbcol);
;   }
.LBB0_738:
	s_barrier
	s_andn2_b64 vcc, exec, s[34:35]
	s_mov_b32 s8, s51
	s_cbranch_vccz .LBB0_1518

; #define STAGE_A(P, br, kt) do { const char* _base = (const char*)(((kt) < G.ksplit ? G.A1 : A2m) + (long)(br) * G.lda + (long)(kt) * BK); \
;     __builtin_amdgcn_global_load_lds((const unsigned*)(_base + aoff0), (unsigned*)((char*)(P) + sb0), 16, 0, 0); \
;     __builtin_amdgcn_global_load_lds((const unsigned*)(_base + aoff1), (unsigned*)((char*)(P) + sb1), 16, 0, 0); } while (0)
; #define LDA(dst, b, h) for (int m = 0; m < 4; ++m) for (int k = 0; k < 2; ++k) \
;     dst[m][k] = *reinterpret_cast<const bf16x8*>(a_rd + ((b) * 2 + (h)) * (HT * 2) + m * 2048 + k * 1024)
; #define LDB(dst, b, h) for (int n = 0; n < 2; ++n) for (int k = 0; k < 2; ++k) \
;     dst[n][k] = *reinterpret_cast<const bf16x8*>(b_rd + ((b) * 2 + (h)) * (HT * 2) + n * 2048 + k * 1024)
; #define MMA(ai, bj, At_, Bt_) do { __builtin_amdgcn_s_setprio(1); \
;     for (int m = 0; m < 4; ++m) for (int n = 0; n < 2; ++n) for (int k = 0; k < 2; ++k) \
;       acc[ai][bj][m][n] = __builtin_amdgcn_mfma_f32_16x16x32_bf16(Bt_[n][k], At_[m][k], acc[ai][bj][m][n], 0, 0, 0); \
;     __builtin_amdgcn_s_setprio(0); } while (0)
; #define WAIT_V(n) asm volatile("s_waitcnt vmcnt(" #n ")" ::: "memory")
; #define WAIT_L(n) asm volatile("s_waitcnt lgkmcnt(" #n ")" ::: "memory")
; #define BAR __builtin_amdgcn_s_barrier()
;     ...
;   float ssv[2][4] = {};
;   if constexpr (EPI == EPI_GU || EPI == EPI_EVIN || EPI == EPI_ODIN) {
; #pragma unroll
;     for (int ai = 0; ai < 2; ++ai)
; #pragma unroll
;       for (int m = 0; m < 4; ++m) ssv[ai][m] = G.ssr[brow + ai * HALF + wr * 64 + m * 16 + fr];
;   }
;   { LDB(B0, 0, 0); LDA(At, 0, 0); STAGE_A(SA(1, 1), brow + HALF, nt - 1);
;     BAR; WAIT_L(0); MMA(0, 0, At, B0); BAR;
;     LDB(B1, 0, 1); BAR; WAIT_L(0); MMA(0, 1, At, B1); BAR;
;     LDA(At, 0, 1); WAIT_V(4); BAR; WAIT_L(0); MMA(1, 0, At, B0); MMA(1, 1, At, B1); BAR; }
.Lmy_kexit_0:
	s_waitcnt vmcnt(6)
	v_not_b32_e32 v250, 63
	v_mov_b32_e32 v251, 0x41b17218
	v_or_b32_e32 v130, s40, v150
	v_lshl_add_u32 v130, v148, 6, v130
	v_ashrrev_i32_e32 v131, 31, v130
	v_lshl_add_u64 v[132:133], v[130:131], 2, s[30:31]
	v_add_u32_e32 v134, 0x80, v130
	v_add_u32_e32 v136, 0x90, v130
	v_add_u32_e32 v138, 0xa0, v130
	v_add_u32_e32 v130, 0xb0, v130
	s_or_b32 s57, s40, 0x80
	v_ashrrev_i32_e32 v135, 31, v134
	v_ashrrev_i32_e32 v137, 31, v136
	v_ashrrev_i32_e32 v139, 31, v138
	v_ashrrev_i32_e32 v131, 31, v130
	s_mul_i32 s8, s57, 0x1080
	v_lshl_add_u64 v[134:135], v[134:135], 2, s[30:31]
	v_lshl_add_u64 v[136:137], v[136:137], 2, s[30:31]
	v_lshl_add_u64 v[138:139], v[138:139], 2, s[30:31]
	v_lshl_add_u64 v[140:141], v[130:131], 2, s[30:31]
	global_load_dword v130, v[132:133], off
	global_load_dword v146, v[132:133], off offset:64
	global_load_dword v148, v[132:133], off offset:128
	global_load_dword v156, v[132:133], off offset:192
	global_load_dword v154, v[134:135], off
	global_load_dword v153, v[136:137], off
	global_load_dword v152, v[138:139], off
	global_load_dword v150, v[140:141], off
	s_mul_hi_i32 s9, s57, 0x1080
	s_add_u32 s8, s12, s8
	s_addc_u32 s9, s13, s9
	v_lshl_add_u64 v[140:141], s[8:9], 0, v[180:181]
	s_mov_b64 s[22:23], 0xf80
	v_readfirstlane_b32 s10, v162
	v_lshl_add_u64 v[140:141], v[140:141], 0, s[22:23]
	s_mov_b32 m0, s10
	ds_read_b128 v[132:135], v155
	ds_read_b128 v[136:139], v155 offset:1024
	ds_read_b128 v[164:167], v155 offset:2048
	ds_read_b128 v[168:171], v155 offset:3072
	ds_read_b128 v[172:175], v151
	ds_read_b128 v[176:179], v151 offset:1024
	ds_read_b128 v[182:185], v151 offset:2048
	ds_read_b128 v[186:189], v151 offset:3072
	ds_read_b128 v[190:193], v151 offset:4096
	ds_read_b128 v[194:197], v151 offset:5120
	ds_read_b128 v[198:201], v151 offset:6144
	ds_read_b128 v[202:205], v151 offset:7168
	global_load_lds_dwordx4 v[140:141], off
	v_lshl_add_u64 v[140:141], s[8:9], 0, v[128:129]
	v_readfirstlane_b32 s8, v163
	v_lshl_add_u64 v[140:141], v[140:141], 0, s[22:23]
	s_mov_b32 m0, s8
	s_nop 0
	global_load_lds_dwordx4 v[140:141], off
	s_barrier
	s_waitcnt lgkmcnt(0)
	s_setprio 1
	s_waitcnt lgkmcnt(0)
	v_mfma_f32_16x16x32_bf16 v[124:127], v[132:135], v[172:175], v[124:127]
	v_mfma_f32_16x16x32_bf16 v[120:123], v[164:167], v[172:175], v[120:123]
	v_mfma_f32_16x16x32_bf16 v[116:119], v[132:135], v[182:185], v[116:119]
	v_mfma_f32_16x16x32_bf16 v[112:115], v[164:167], v[182:185], v[112:115]
	v_mfma_f32_16x16x32_bf16 v[108:111], v[132:135], v[190:193], v[108:111]
	v_mfma_f32_16x16x32_bf16 v[104:107], v[164:167], v[190:193], v[104:107]
	v_mfma_f32_16x16x32_bf16 v[100:103], v[132:135], v[198:201], v[100:103]
	v_mfma_f32_16x16x32_bf16 v[96:99], v[164:167], v[198:201], v[96:99]
	v_mfma_f32_16x16x32_bf16 v[124:127], v[136:139], v[176:179], v[124:127]
	v_mfma_f32_16x16x32_bf16 v[120:123], v[168:171], v[176:179], v[120:123]
	v_mfma_f32_16x16x32_bf16 v[116:119], v[136:139], v[186:189], v[116:119]
	v_mfma_f32_16x16x32_bf16 v[112:115], v[168:171], v[186:189], v[112:115]
	v_mfma_f32_16x16x32_bf16 v[108:111], v[136:139], v[194:197], v[108:111]
	v_mfma_f32_16x16x32_bf16 v[104:107], v[168:171], v[194:197], v[104:107]
	s_setprio 2
	s_barrier
	v_mfma_f32_16x16x32_bf16 v[100:103], v[136:139], v[202:205], v[100:103]
	v_mfma_f32_16x16x32_bf16 v[96:99], v[168:171], v[202:205], v[96:99]
	s_setprio 0
	ds_read_b128 v[206:209], v155 offset:16384
	ds_read_b128 v[210:213], v155 offset:17408
	ds_read_b128 v[214:217], v155 offset:18432
	ds_read_b128 v[218:221], v155 offset:19456
	s_barrier
	s_waitcnt lgkmcnt(0)
	s_setprio 1
	s_waitcnt lgkmcnt(0)
	v_mfma_f32_16x16x32_bf16 v[92:95], v[206:209], v[172:175], v[92:95]
	v_mfma_f32_16x16x32_bf16 v[88:91], v[214:217], v[172:175], v[88:91]
	v_mfma_f32_16x16x32_bf16 v[84:87], v[206:209], v[182:185], v[84:87]
	v_mfma_f32_16x16x32_bf16 v[80:83], v[214:217], v[182:185], v[80:83]
	v_mfma_f32_16x16x32_bf16 v[76:79], v[206:209], v[190:193], v[76:79]
	v_mfma_f32_16x16x32_bf16 v[72:75], v[214:217], v[190:193], v[72:75]
	v_mfma_f32_16x16x32_bf16 v[68:71], v[206:209], v[198:201], v[68:71]
	v_mfma_f32_16x16x32_bf16 v[64:67], v[214:217], v[198:201], v[64:67]
	v_mfma_f32_16x16x32_bf16 v[92:95], v[210:213], v[176:179], v[92:95]
	v_mfma_f32_16x16x32_bf16 v[88:91], v[218:221], v[176:179], v[88:91]
	v_mfma_f32_16x16x32_bf16 v[84:87], v[210:213], v[186:189], v[84:87]
	v_mfma_f32_16x16x32_bf16 v[80:83], v[218:221], v[186:189], v[80:83]
	v_mfma_f32_16x16x32_bf16 v[76:79], v[210:213], v[194:197], v[76:79]
	v_mfma_f32_16x16x32_bf16 v[72:75], v[218:221], v[194:197], v[72:75]
	s_setprio 2
	s_barrier
	v_mfma_f32_16x16x32_bf16 v[68:71], v[210:213], v[202:205], v[68:71]
	v_mfma_f32_16x16x32_bf16 v[64:67], v[218:221], v[202:205], v[64:67]
	s_setprio 0
	ds_read_b128 v[172:175], v151 offset:16384
	ds_read_b128 v[176:179], v151 offset:17408
	ds_read_b128 v[182:185], v151 offset:18432
	ds_read_b128 v[186:189], v151 offset:19456
	ds_read_b128 v[190:193], v151 offset:20480
	ds_read_b128 v[194:197], v151 offset:21504
	ds_read_b128 v[198:201], v151 offset:22528
	ds_read_b128 v[202:205], v151 offset:23552
	s_waitcnt vmcnt(4)
	s_barrier
; #define STAGE_A(P, br, kt) do { const char* _base = (const char*)(((kt) < G.ksplit ? G.A1 : A2m) + (long)(br) * G.lda + (long)(kt) * BK); \
;     __builtin_amdgcn_global_load_lds((const unsigned*)(_base + aoff0), (unsigned*)((char*)(P) + sb0), 16, 0, 0); \
;     __builtin_amdgcn_global_load_lds((const unsigned*)(_base + aoff1), (unsigned*)((char*)(P) + sb1), 16, 0, 0); } while (0)
; #define LDA(dst, b, h) for (int m = 0; m < 4; ++m) for (int k = 0; k < 2; ++k) \
;     dst[m][k] = *reinterpret_cast<const bf16x8*>(a_rd + ((b) * 2 + (h)) * (HT * 2) + m * 2048 + k * 1024)
; #define LDB(dst, b, h) for (int n = 0; n < 2; ++n) for (int k = 0; k < 2; ++k) \
;     dst[n][k] = *reinterpret_cast<const bf16x8*>(b_rd + ((b) * 2 + (h)) * (HT * 2) + n * 2048 + k * 1024)
; #define MMA(ai, bj, At_, Bt_) do { __builtin_amdgcn_s_setprio(1); \
;     for (int m = 0; m < 4; ++m) for (int n = 0; n < 2; ++n) for (int k = 0; k < 2; ++k) \
;       acc[ai][bj][m][n] = __builtin_amdgcn_mfma_f32_16x16x32_bf16(Bt_[n][k], At_[m][k], acc[ai][bj][m][n], 0, 0, 0); \
;     __builtin_amdgcn_s_setprio(0); } while (0)
; #define WAIT_V(n) asm volatile("s_waitcnt vmcnt(" #n ")" ::: "memory")
; #define WAIT_L(n) asm volatile("s_waitcnt lgkmcnt(" #n ")" ::: "memory")
; #define BAR __builtin_amdgcn_s_barrier()
;     ...
;   { LDB(B0, 0, 0); LDA(At, 0, 0); STAGE_A(SA(1, 1), brow + HALF, nt - 1);
;     BAR; WAIT_L(0); MMA(0, 0, At, B0); BAR;
;     LDB(B1, 0, 1); BAR; WAIT_L(0); MMA(0, 1, At, B1); BAR;
;     LDA(At, 0, 1); WAIT_V(4); BAR; WAIT_L(0); MMA(1, 0, At, B0); MMA(1, 1, At, B1); BAR; }
;   { LDB(B0, 1, 0); LDA(At, 1, 0); WAIT_V(2); BAR; WAIT_L(0); MMA(0, 0, At, B0); BAR;
;     LDB(B1, 1, 1); WAIT_V(0); BAR; WAIT_L(0); MMA(0, 1, At, B1); BAR;
;     LDA(At, 1, 1); BAR; WAIT_L(0); MMA(1, 0, At, B0); MMA(1, 1, At, B1); BAR; }
	s_waitcnt lgkmcnt(0)
	s_setprio 1
	s_waitcnt lgkmcnt(0)
	v_mfma_f32_16x16x32_bf16 v[60:63], v[132:135], v[172:175], v[60:63]
	v_mfma_f32_16x16x32_bf16 v[56:59], v[164:167], v[172:175], v[56:59]
	v_mfma_f32_16x16x32_bf16 v[52:55], v[132:135], v[182:185], v[52:55]
	v_mfma_f32_16x16x32_bf16 v[48:51], v[164:167], v[182:185], v[48:51]
	v_mfma_f32_16x16x32_bf16 v[44:47], v[132:135], v[190:193], v[44:47]
	v_mfma_f32_16x16x32_bf16 v[40:43], v[164:167], v[190:193], v[40:43]
	v_mfma_f32_16x16x32_bf16 v[36:39], v[132:135], v[198:201], v[36:39]
	v_mfma_f32_16x16x32_bf16 v[32:35], v[164:167], v[198:201], v[32:35]
	v_mfma_f32_16x16x32_bf16 v[60:63], v[136:139], v[176:179], v[60:63]
	v_mfma_f32_16x16x32_bf16 v[56:59], v[168:171], v[176:179], v[56:59]
	v_mfma_f32_16x16x32_bf16 v[52:55], v[136:139], v[186:189], v[52:55]
	v_mfma_f32_16x16x32_bf16 v[48:51], v[168:171], v[186:189], v[48:51]
	v_mfma_f32_16x16x32_bf16 v[44:47], v[136:139], v[194:197], v[44:47]
	v_mfma_f32_16x16x32_bf16 v[40:43], v[168:171], v[194:197], v[40:43]
	v_mfma_f32_16x16x32_bf16 v[36:39], v[136:139], v[202:205], v[36:39]
	v_mfma_f32_16x16x32_bf16 v[32:35], v[168:171], v[202:205], v[32:35]
	s_setprio 0
	s_setprio 1
	v_mfma_f32_16x16x32_bf16 v[28:31], v[206:209], v[172:175], v[28:31]
	v_mfma_f32_16x16x32_bf16 v[24:27], v[214:217], v[172:175], v[24:27]
	v_mfma_f32_16x16x32_bf16 v[20:23], v[206:209], v[182:185], v[20:23]
	v_mfma_f32_16x16x32_bf16 v[16:19], v[214:217], v[182:185], v[16:19]
	v_mfma_f32_16x16x32_bf16 v[12:15], v[206:209], v[190:193], v[12:15]
	v_mfma_f32_16x16x32_bf16 v[8:11], v[214:217], v[190:193], v[8:11]
	v_mfma_f32_16x16x32_bf16 v[4:7], v[206:209], v[198:201], v[4:7]
	v_mfma_f32_16x16x32_bf16 v[0:3], v[214:217], v[198:201], v[0:3]
	v_mfma_f32_16x16x32_bf16 v[28:31], v[210:213], v[176:179], v[28:31]
	v_mfma_f32_16x16x32_bf16 v[24:27], v[218:221], v[176:179], v[24:27]
	v_mfma_f32_16x16x32_bf16 v[20:23], v[210:213], v[186:189], v[20:23]
	v_mfma_f32_16x16x32_bf16 v[16:19], v[218:221], v[186:189], v[16:19]
	v_mfma_f32_16x16x32_bf16 v[12:15], v[210:213], v[194:197], v[12:15]
	v_mfma_f32_16x16x32_bf16 v[8:11], v[218:221], v[194:197], v[8:11]
	s_setprio 2
	s_barrier
	v_mfma_f32_16x16x32_bf16 v[4:7], v[210:213], v[202:205], v[4:7]
	v_mfma_f32_16x16x32_bf16 v[0:3], v[218:221], v[202:205], v[0:3]
	s_setprio 0
	ds_read_b128 v[132:135], v155 offset:32768
	ds_read_b128 v[136:139], v155 offset:33792
	ds_read_b128 v[162:165], v155 offset:34816
	ds_read_b128 v[166:169], v155 offset:35840
	ds_read_b128 v[170:173], v151 offset:32768
	ds_read_b128 v[174:177], v151 offset:33792
	ds_read_b128 v[182:185], v151 offset:34816
	ds_read_b128 v[186:189], v151 offset:35840
	ds_read_b128 v[190:193], v151 offset:36864
	ds_read_b128 v[194:197], v151 offset:37888
	ds_read_b128 v[198:201], v151 offset:38912
	ds_read_b128 v[202:205], v151 offset:39936
	s_waitcnt vmcnt(2)
	s_barrier
	s_waitcnt lgkmcnt(0)
	s_setprio 1
	s_waitcnt lgkmcnt(0)
	v_mfma_f32_16x16x32_bf16 v[124:127], v[132:135], v[170:173], v[124:127]
	v_mfma_f32_16x16x32_bf16 v[120:123], v[162:165], v[170:173], v[120:123]
	v_mfma_f32_16x16x32_bf16 v[116:119], v[132:135], v[182:185], v[116:119]
	v_mfma_f32_16x16x32_bf16 v[112:115], v[162:165], v[182:185], v[112:115]
	v_mfma_f32_16x16x32_bf16 v[108:111], v[132:135], v[190:193], v[108:111]
	v_mfma_f32_16x16x32_bf16 v[104:107], v[162:165], v[190:193], v[104:107]
	v_mfma_f32_16x16x32_bf16 v[100:103], v[132:135], v[198:201], v[100:103]
	v_mfma_f32_16x16x32_bf16 v[96:99], v[162:165], v[198:201], v[96:99]
	v_mfma_f32_16x16x32_bf16 v[124:127], v[136:139], v[174:177], v[124:127]
	v_mfma_f32_16x16x32_bf16 v[120:123], v[166:169], v[174:177], v[120:123]
	v_mfma_f32_16x16x32_bf16 v[116:119], v[136:139], v[186:189], v[116:119]
	v_mfma_f32_16x16x32_bf16 v[112:115], v[166:169], v[186:189], v[112:115]
	v_mfma_f32_16x16x32_bf16 v[108:111], v[136:139], v[194:197], v[108:111]
	v_mfma_f32_16x16x32_bf16 v[104:107], v[166:169], v[194:197], v[104:107]
	s_setprio 2
	s_barrier
	v_mfma_f32_16x16x32_bf16 v[100:103], v[136:139], v[202:205], v[100:103]
	v_mfma_f32_16x16x32_bf16 v[96:99], v[166:169], v[202:205], v[96:99]
	s_setprio 0
	ds_read_b128 v[206:209], v155 offset:49152
	ds_read_b128 v[210:213], v155 offset:50176
	ds_read_b128 v[214:217], v155 offset:51200
	ds_read_b128 v[218:221], v155 offset:52224
	s_waitcnt vmcnt(0)
	s_barrier
	s_waitcnt lgkmcnt(0)
	s_setprio 1
	s_waitcnt lgkmcnt(0)
	v_mfma_f32_16x16x32_bf16 v[92:95], v[206:209], v[170:173], v[92:95]
	v_mfma_f32_16x16x32_bf16 v[88:91], v[214:217], v[170:173], v[88:91]
	v_mfma_f32_16x16x32_bf16 v[84:87], v[206:209], v[182:185], v[84:87]
	v_mfma_f32_16x16x32_bf16 v[80:83], v[214:217], v[182:185], v[80:83]
	v_mfma_f32_16x16x32_bf16 v[76:79], v[206:209], v[190:193], v[76:79]
	v_mfma_f32_16x16x32_bf16 v[72:75], v[214:217], v[190:193], v[72:75]
	v_mfma_f32_16x16x32_bf16 v[68:71], v[206:209], v[198:201], v[68:71]
	v_mfma_f32_16x16x32_bf16 v[64:67], v[214:217], v[198:201], v[64:67]
	v_mfma_f32_16x16x32_bf16 v[92:95], v[210:213], v[174:177], v[92:95]
	v_mfma_f32_16x16x32_bf16 v[88:91], v[218:221], v[174:177], v[88:91]
	v_mfma_f32_16x16x32_bf16 v[84:87], v[210:213], v[186:189], v[84:87]
	v_mfma_f32_16x16x32_bf16 v[80:83], v[218:221], v[186:189], v[80:83]
	v_mfma_f32_16x16x32_bf16 v[76:79], v[210:213], v[194:197], v[76:79]
	v_mfma_f32_16x16x32_bf16 v[72:75], v[218:221], v[194:197], v[72:75]
	s_setprio 2
	s_barrier
; #define STAGE_A(P, br, kt) do { const char* _base = (const char*)(((kt) < G.ksplit ? G.A1 : A2m) + (long)(br) * G.lda + (long)(kt) * BK); \
;     __builtin_amdgcn_global_load_lds((const unsigned*)(_base + aoff0), (unsigned*)((char*)(P) + sb0), 16, 0, 0); \
;     __builtin_amdgcn_global_load_lds((const unsigned*)(_base + aoff1), (unsigned*)((char*)(P) + sb1), 16, 0, 0); } while (0)
; #define STAGE_B(P, br, kt) do { const char* _base = (const char*)(G.Bt + (long)(br) * G.ldb + (long)(kt) * BK); \
;     __builtin_amdgcn_global_load_lds((const unsigned*)(_base + boff0), (unsigned*)((char*)(P) + sb0), 16, 0, 0); \
;     __builtin_amdgcn_global_load_lds((const unsigned*)(_base + boff1), (unsigned*)((char*)(P) + sb1), 16, 0, 0); } while (0)
; #define LDA(dst, b, h) for (int m = 0; m < 4; ++m) for (int k = 0; k < 2; ++k) \
;     dst[m][k] = *reinterpret_cast<const bf16x8*>(a_rd + ((b) * 2 + (h)) * (HT * 2) + m * 2048 + k * 1024)
; #define LDB(dst, b, h) for (int n = 0; n < 2; ++n) for (int k = 0; k < 2; ++k) \
;     dst[n][k] = *reinterpret_cast<const bf16x8*>(b_rd + ((b) * 2 + (h)) * (HT * 2) + n * 2048 + k * 1024)
; #define MMA(ai, bj, At_, Bt_) do { __builtin_amdgcn_s_setprio(1); \
;     for (int m = 0; m < 4; ++m) for (int n = 0; n < 2; ++n) for (int k = 0; k < 2; ++k) \
;       acc[ai][bj][m][n] = __builtin_amdgcn_mfma_f32_16x16x32_bf16(Bt_[n][k], At_[m][k], acc[ai][bj][m][n], 0, 0, 0); \
;     __builtin_amdgcn_s_setprio(0); } while (0)
; #define WAIT_V(n) asm volatile("s_waitcnt vmcnt(" #n ")" ::: "memory")
; #define WAIT_L(n) asm volatile("s_waitcnt lgkmcnt(" #n ")" ::: "memory")
; #define BAR __builtin_amdgcn_s_barrier()
;     ...
;   { LDB(B0, 1, 0); LDA(At, 1, 0); WAIT_V(2); BAR; WAIT_L(0); MMA(0, 0, At, B0); BAR;
;     LDB(B1, 1, 1); WAIT_V(0); BAR; WAIT_L(0); MMA(0, 1, At, B1); BAR;
;     LDA(At, 1, 1); BAR; WAIT_L(0); MMA(1, 0, At, B0); MMA(1, 1, At, B1); BAR; }
;   if (wr == 0) BAR;
;   if (EPI != EPI_RESID && has_next) {
;     STAGE_B(SB(0, 0), nbcol, 0); STAGE_A(SA(0, 0), nbrow, 0);
;     STAGE_B(SB(0, 1), nbcol + HALF, 0); STAGE_A(SA(0, 1), nbrow + HALF, 0);
;   }
	v_mfma_f32_16x16x32_bf16 v[68:71], v[210:213], v[202:205], v[68:71]
	v_mfma_f32_16x16x32_bf16 v[64:67], v[218:221], v[202:205], v[64:67]
	s_setprio 0
	ds_read_b128 v[170:173], v151 offset:49152
	ds_read_b128 v[174:177], v151 offset:50176
	ds_read_b128 v[182:185], v151 offset:51200
	ds_read_b128 v[186:189], v151 offset:52224
	ds_read_b128 v[190:193], v151 offset:53248
	ds_read_b128 v[194:197], v151 offset:54272
	ds_read_b128 v[198:201], v151 offset:55296
	ds_read_b128 v[202:205], v151 offset:56320
	s_barrier
	s_waitcnt lgkmcnt(0)
	s_setprio 1
	s_waitcnt lgkmcnt(0)
	v_mfma_f32_16x16x32_bf16 v[60:63], v[132:135], v[170:173], v[60:63]
	v_mfma_f32_16x16x32_bf16 v[56:59], v[162:165], v[170:173], v[56:59]
	v_mfma_f32_16x16x32_bf16 v[52:55], v[132:135], v[182:185], v[52:55]
	v_mfma_f32_16x16x32_bf16 v[48:51], v[162:165], v[182:185], v[48:51]
	v_mfma_f32_16x16x32_bf16 v[44:47], v[132:135], v[190:193], v[44:47]
	v_mfma_f32_16x16x32_bf16 v[40:43], v[162:165], v[190:193], v[40:43]
	v_mfma_f32_16x16x32_bf16 v[36:39], v[132:135], v[198:201], v[36:39]
	v_mfma_f32_16x16x32_bf16 v[32:35], v[162:165], v[198:201], v[32:35]
	v_mfma_f32_16x16x32_bf16 v[60:63], v[136:139], v[174:177], v[60:63]
	v_mfma_f32_16x16x32_bf16 v[56:59], v[166:169], v[174:177], v[56:59]
	v_mfma_f32_16x16x32_bf16 v[52:55], v[136:139], v[186:189], v[52:55]
	v_mfma_f32_16x16x32_bf16 v[48:51], v[166:169], v[186:189], v[48:51]
	v_mfma_f32_16x16x32_bf16 v[44:47], v[136:139], v[194:197], v[44:47]
	v_mfma_f32_16x16x32_bf16 v[40:43], v[166:169], v[194:197], v[40:43]
	v_mfma_f32_16x16x32_bf16 v[36:39], v[136:139], v[202:205], v[36:39]
	v_mfma_f32_16x16x32_bf16 v[32:35], v[166:169], v[202:205], v[32:35]
	s_setprio 0
	s_setprio 1
	v_mfma_f32_16x16x32_bf16 v[28:31], v[206:209], v[170:173], v[28:31]
	v_mfma_f32_16x16x32_bf16 v[24:27], v[214:217], v[170:173], v[24:27]
	v_mfma_f32_16x16x32_bf16 v[20:23], v[206:209], v[182:185], v[20:23]
	v_mfma_f32_16x16x32_bf16 v[16:19], v[214:217], v[182:185], v[16:19]
	v_mfma_f32_16x16x32_bf16 v[12:15], v[206:209], v[190:193], v[12:15]
	v_mfma_f32_16x16x32_bf16 v[8:11], v[214:217], v[190:193], v[8:11]
	v_mfma_f32_16x16x32_bf16 v[4:7], v[206:209], v[198:201], v[4:7]
	v_mfma_f32_16x16x32_bf16 v[0:3], v[214:217], v[198:201], v[0:3]
	v_mfma_f32_16x16x32_bf16 v[28:31], v[210:213], v[174:177], v[28:31]
	v_mfma_f32_16x16x32_bf16 v[24:27], v[218:221], v[174:177], v[24:27]
	v_mfma_f32_16x16x32_bf16 v[20:23], v[210:213], v[186:189], v[20:23]
	v_mfma_f32_16x16x32_bf16 v[16:19], v[218:221], v[186:189], v[16:19]
	v_readfirstlane_b32 s8, v224
	v_mfma_f32_16x16x32_bf16 v[12:15], v[210:213], v[194:197], v[12:15]
	v_mfma_f32_16x16x32_bf16 v[8:11], v[218:221], v[194:197], v[8:11]
	s_setprio 2
	s_bitcmp0_b32 s8, 8
	s_cbranch_scc0 .Lmy_t6skip_1
	s_barrier
.Lmy_t6skip_1:
	v_mfma_f32_16x16x32_bf16 v[4:7], v[210:213], v[202:205], v[4:7]
	v_mfma_f32_16x16x32_bf16 v[0:3], v[218:221], v[202:205], v[0:3]
	s_setprio 0
	s_andn2_b64 vcc, exec, s[6:7]
	s_cbranch_vccnz .LBB0_751
	s_mul_i32 s6, s41, 0x840
	s_ashr_i32 s7, s6, 31
	s_lshl_b64 s[6:7], s[6:7], 1
	s_add_u32 s6, s49, s6
	s_addc_u32 s7, s50, s7
	v_readfirstlane_b32 s8, v159
	v_lshl_add_u64 v[132:133], s[6:7], 0, v[180:181]
	s_mov_b32 m0, s8
	s_mul_i32 s8, s38, 0x1080
	global_load_lds_dwordx4 v[132:133], off
	v_lshl_add_u64 v[132:133], s[6:7], 0, v[128:129]
	v_readfirstlane_b32 s6, v160
	s_mov_b32 m0, s6
	s_mul_hi_i32 s7, s38, 0x1080
	s_add_u32 s6, s12, s8
	s_addc_u32 s7, s13, s7
	v_readfirstlane_b32 s9, v149
	global_load_lds_dwordx4 v[132:133], off
	v_lshl_add_u64 v[132:133], s[6:7], 0, v[180:181]
	s_mov_b32 m0, s9
	v_readfirstlane_b32 s9, v145
	global_load_lds_dwordx4 v[132:133], off
	v_lshl_add_u64 v[132:133], s[6:7], 0, v[128:129]
	v_readfirstlane_b32 s6, v147
	s_mov_b32 m0, s6
	s_or_b32 s6, s41, 0x80
	s_mul_hi_i32 s7, s6, 0x1080
	s_mulk_i32 s6, 0x1080
	s_add_u32 s6, s49, s6
	s_addc_u32 s7, s50, s7
	global_load_lds_dwordx4 v[132:133], off
	v_lshl_add_u64 v[132:133], s[6:7], 0, v[180:181]
	s_mov_b32 m0, s9
	s_add_i32 s8, s8, 0x84000
	global_load_lds_dwordx4 v[132:133], off
	v_lshl_add_u64 v[132:133], s[6:7], 0, v[128:129]
	v_readfirstlane_b32 s6, v161
	s_mov_b32 m0, s6
	s_add_i32 s6, s38, 0x80
	s_mul_hi_i32 s7, s6, 0x1080
	s_add_u32 s6, s12, s8
	s_addc_u32 s7, s13, s7
	v_readfirstlane_b32 s8, v143
	global_load_lds_dwordx4 v[132:133], off
	v_lshl_add_u64 v[132:133], s[6:7], 0, v[180:181]
	s_mov_b32 m0, s8
	v_lshl_add_u64 v[128:129], s[6:7], 0, v[128:129]
	v_readfirstlane_b32 s6, v142
	global_load_lds_dwordx4 v[132:133], off
	s_mov_b32 m0, s6
	s_nop 0
	global_load_lds_dwordx4 v[128:129], off

; template <int EPI>
; __device__ __forceinline__ void gemm_phase(const GemmArgs& G, char* shm) {
;     ...
;   for (int t = vb; t < nwg; t += gridDim.x) {
;     int brow, bcol, nbrow = 0, nbcol = 0; gemm_map_tile(G, t, brow, bcol);
;     const bool has_next = t + (int)gridDim.x < nwg;
;     if (has_next) gemm_map_tile(G, t + gridDim.x, nbrow, nbcol);
;     gemm_tile<EPI>(G, brow, bcol, shm, t == vb, has_next, nbrow, nbcol);
.LBB0_1856:
	global_store_dwordx2 v[2:3], v[0:1], off
	s_barrier
	s_andn2_b64 vcc, exec, s[22:23]
	s_mov_b32 s24, s41
	s_cbranch_vccz .LBB0_2254

; #define STAGE_A(P, br, kt) do { const char* _base = (const char*)(((kt) < G.ksplit ? G.A1 : A2m) + (long)(br) * G.lda + (long)(kt) * BK); \
;     __builtin_amdgcn_global_load_lds((const unsigned*)(_base + aoff0), (unsigned*)((char*)(P) + sb0), 16, 0, 0); \
;     __builtin_amdgcn_global_load_lds((const unsigned*)(_base + aoff1), (unsigned*)((char*)(P) + sb1), 16, 0, 0); } while (0)
; #define LDA(dst, b, h) for (int m = 0; m < 4; ++m) for (int k = 0; k < 2; ++k) \
;     dst[m][k] = *reinterpret_cast<const bf16x8*>(a_rd + ((b) * 2 + (h)) * (HT * 2) + m * 2048 + k * 1024)
; #define LDB(dst, b, h) for (int n = 0; n < 2; ++n) for (int k = 0; k < 2; ++k) \
;     dst[n][k] = *reinterpret_cast<const bf16x8*>(b_rd + ((b) * 2 + (h)) * (HT * 2) + n * 2048 + k * 1024)
; #define MMA(ai, bj, At_, Bt_) do { __builtin_amdgcn_s_setprio(1); \
;     for (int m = 0; m < 4; ++m) for (int n = 0; n < 2; ++n) for (int k = 0; k < 2; ++k) \
;       acc[ai][bj][m][n] = __builtin_amdgcn_mfma_f32_16x16x32_bf16(Bt_[n][k], At_[m][k], acc[ai][bj][m][n], 0, 0, 0); \
;     __builtin_amdgcn_s_setprio(0); } while (0)
; #define WAIT_V(n) asm volatile("s_waitcnt vmcnt(" #n ")" ::: "memory")
; #define WAIT_L(n) asm volatile("s_waitcnt lgkmcnt(" #n ")" ::: "memory")
; #define BAR __builtin_amdgcn_s_barrier()
;     ...
;   float ssv[2][4] = {};
;   if constexpr (EPI == EPI_GU || EPI == EPI_EVIN || EPI == EPI_ODIN) {
; #pragma unroll
;     for (int ai = 0; ai < 2; ++ai)
; #pragma unroll
;       for (int m = 0; m < 4; ++m) ssv[ai][m] = G.ssr[brow + ai * HALF + wr * 64 + m * 16 + fr];
;   }
;   { LDB(B0, 0, 0); LDA(At, 0, 0); STAGE_A(SA(1, 1), brow + HALF, nt - 1);
;     BAR; WAIT_L(0); MMA(0, 0, At, B0); BAR;
;     LDB(B1, 0, 1); BAR; WAIT_L(0); MMA(0, 1, At, B1); BAR;
;     LDA(At, 0, 1); WAIT_V(4); BAR; WAIT_L(0); MMA(1, 0, At, B0); MMA(1, 1, At, B1); BAR; }
.Lmy_kexit_2:
	s_waitcnt vmcnt(6)
	v_not_b32_e32 v250, 63
	v_mov_b32_e32 v251, 0x41b17218
	v_or_b32_e32 v130, s29, v144
	v_lshl_add_u32 v130, v143, 6, v130
	v_ashrrev_i32_e32 v131, 31, v130
	v_add_u32_e32 v142, 0xa0, v130
	v_lshl_add_u64 v[132:133], v[130:131], 2, s[20:21]
	v_add_u32_e32 v134, 0x80, v130
	v_add_u32_e32 v136, 0x90, v130
	v_ashrrev_i32_e32 v143, 31, v142
	v_add_u32_e32 v130, 0xb0, v130
	s_or_b32 s42, s29, 0x80
	v_ashrrev_i32_e32 v135, 31, v134
	v_ashrrev_i32_e32 v137, 31, v136
	v_lshl_add_u64 v[142:143], v[142:143], 2, s[20:21]
	v_ashrrev_i32_e32 v131, 31, v130
	s_mul_i32 s26, s42, 0x1080
	v_lshl_add_u64 v[134:135], v[134:135], 2, s[20:21]
	v_lshl_add_u64 v[136:137], v[136:137], 2, s[20:21]
	v_lshl_add_u64 v[160:161], v[130:131], 2, s[20:21]
	global_load_dword v130, v[132:133], off
	global_load_dword v152, v[132:133], off offset:64
	global_load_dword v151, v[132:133], off offset:128
	global_load_dword v150, v[132:133], off offset:192
	global_load_dword v145, v[134:135], off
	global_load_dword v144, v[136:137], off
	s_nop 0
	global_load_dword v143, v[142:143], off
	s_nop 0
	global_load_dword v142, v[160:161], off
	s_mul_hi_i32 s27, s42, 0x1080
	s_add_u32 s26, s37, s26
	s_addc_u32 s27, s38, s27
	v_lshl_add_u64 v[136:137], s[26:27], 0, v[180:181]
	s_mov_b64 s[44:45], 0xf80
	v_readfirstlane_b32 s30, v158
	v_lshl_add_u64 v[136:137], v[136:137], 0, s[44:45]
	s_mov_b32 m0, s30
	ds_read_b128 v[132:135], v149
	ds_read_b128 v[160:163], v149 offset:1024
	ds_read_b128 v[164:167], v149 offset:2048
	ds_read_b128 v[168:171], v149 offset:3072
	ds_read_b128 v[172:175], v148
	ds_read_b128 v[176:179], v148 offset:1024
	ds_read_b128 v[182:185], v148 offset:2048
	ds_read_b128 v[186:189], v148 offset:3072
	ds_read_b128 v[190:193], v148 offset:4096
	ds_read_b128 v[194:197], v148 offset:5120
	ds_read_b128 v[198:201], v148 offset:6144
	ds_read_b128 v[202:205], v148 offset:7168
	global_load_lds_dwordx4 v[136:137], off
	v_lshl_add_u64 v[136:137], s[26:27], 0, v[128:129]
	v_readfirstlane_b32 s26, v159
	v_lshl_add_u64 v[136:137], v[136:137], 0, s[44:45]
	s_mov_b32 m0, s26
	s_nop 0
	global_load_lds_dwordx4 v[136:137], off
	s_barrier
	s_waitcnt lgkmcnt(0)
	s_setprio 1
	s_waitcnt lgkmcnt(0)
	v_mfma_f32_16x16x32_bf16 v[124:127], v[132:135], v[172:175], v[124:127]
	v_mfma_f32_16x16x32_bf16 v[120:123], v[164:167], v[172:175], v[120:123]
	v_mfma_f32_16x16x32_bf16 v[116:119], v[132:135], v[182:185], v[116:119]
	v_mfma_f32_16x16x32_bf16 v[112:115], v[164:167], v[182:185], v[112:115]
	v_mfma_f32_16x16x32_bf16 v[108:111], v[132:135], v[190:193], v[108:111]
	v_mfma_f32_16x16x32_bf16 v[104:107], v[164:167], v[190:193], v[104:107]
	v_mfma_f32_16x16x32_bf16 v[100:103], v[132:135], v[198:201], v[100:103]
	v_mfma_f32_16x16x32_bf16 v[96:99], v[164:167], v[198:201], v[96:99]
	v_mfma_f32_16x16x32_bf16 v[124:127], v[160:163], v[176:179], v[124:127]
	v_mfma_f32_16x16x32_bf16 v[120:123], v[168:171], v[176:179], v[120:123]
	v_mfma_f32_16x16x32_bf16 v[116:119], v[160:163], v[186:189], v[116:119]
	v_mfma_f32_16x16x32_bf16 v[112:115], v[168:171], v[186:189], v[112:115]
	v_mfma_f32_16x16x32_bf16 v[108:111], v[160:163], v[194:197], v[108:111]
	v_mfma_f32_16x16x32_bf16 v[104:107], v[168:171], v[194:197], v[104:107]
	s_setprio 2
	s_barrier
	v_mfma_f32_16x16x32_bf16 v[100:103], v[160:163], v[202:205], v[100:103]
	v_mfma_f32_16x16x32_bf16 v[96:99], v[168:171], v[202:205], v[96:99]
	s_setprio 0
	ds_read_b128 v[206:209], v149 offset:16384
	ds_read_b128 v[210:213], v149 offset:17408
	ds_read_b128 v[214:217], v149 offset:18432
	ds_read_b128 v[218:221], v149 offset:19456
	s_barrier
	s_waitcnt lgkmcnt(0)
	s_setprio 1
	s_waitcnt lgkmcnt(0)
	v_mfma_f32_16x16x32_bf16 v[92:95], v[206:209], v[172:175], v[92:95]
	v_mfma_f32_16x16x32_bf16 v[88:91], v[214:217], v[172:175], v[88:91]
	v_mfma_f32_16x16x32_bf16 v[84:87], v[206:209], v[182:185], v[84:87]
	v_mfma_f32_16x16x32_bf16 v[80:83], v[214:217], v[182:185], v[80:83]
	v_mfma_f32_16x16x32_bf16 v[76:79], v[206:209], v[190:193], v[76:79]
	v_mfma_f32_16x16x32_bf16 v[72:75], v[214:217], v[190:193], v[72:75]
	v_mfma_f32_16x16x32_bf16 v[68:71], v[206:209], v[198:201], v[68:71]
	v_mfma_f32_16x16x32_bf16 v[64:67], v[214:217], v[198:201], v[64:67]
	v_mfma_f32_16x16x32_bf16 v[92:95], v[210:213], v[176:179], v[92:95]
	v_mfma_f32_16x16x32_bf16 v[88:91], v[218:221], v[176:179], v[88:91]
	v_mfma_f32_16x16x32_bf16 v[84:87], v[210:213], v[186:189], v[84:87]
	v_mfma_f32_16x16x32_bf16 v[80:83], v[218:221], v[186:189], v[80:83]
	v_mfma_f32_16x16x32_bf16 v[76:79], v[210:213], v[194:197], v[76:79]
	v_mfma_f32_16x16x32_bf16 v[72:75], v[218:221], v[194:197], v[72:75]
	s_setprio 2
	s_barrier
	v_mfma_f32_16x16x32_bf16 v[68:71], v[210:213], v[202:205], v[68:71]
	v_mfma_f32_16x16x32_bf16 v[64:67], v[218:221], v[202:205], v[64:67]
	s_setprio 0
	ds_read_b128 v[172:175], v148 offset:16384
	ds_read_b128 v[176:179], v148 offset:17408
	ds_read_b128 v[182:185], v148 offset:18432
	ds_read_b128 v[186:189], v148 offset:19456
	ds_read_b128 v[190:193], v148 offset:20480
	ds_read_b128 v[194:197], v148 offset:21504
	ds_read_b128 v[198:201], v148 offset:22528
	ds_read_b128 v[202:205], v148 offset:23552
	s_waitcnt vmcnt(4)
	s_barrier
; #define STAGE_A(P, br, kt) do { const char* _base = (const char*)(((kt) < G.ksplit ? G.A1 : A2m) + (long)(br) * G.lda + (long)(kt) * BK); \
;     __builtin_amdgcn_global_load_lds((const unsigned*)(_base + aoff0), (unsigned*)((char*)(P) + sb0), 16, 0, 0); \
;     __builtin_amdgcn_global_load_lds((const unsigned*)(_base + aoff1), (unsigned*)((char*)(P) + sb1), 16, 0, 0); } while (0)
; #define LDA(dst, b, h) for (int m = 0; m < 4; ++m) for (int k = 0; k < 2; ++k) \
;     dst[m][k] = *reinterpret_cast<const bf16x8*>(a_rd + ((b) * 2 + (h)) * (HT * 2) + m * 2048 + k * 1024)
; #define LDB(dst, b, h) for (int n = 0; n < 2; ++n) for (int k = 0; k < 2; ++k) \
;     dst[n][k] = *reinterpret_cast<const bf16x8*>(b_rd + ((b) * 2 + (h)) * (HT * 2) + n * 2048 + k * 1024)
; #define MMA(ai, bj, At_, Bt_) do { __builtin_amdgcn_s_setprio(1); \
;     for (int m = 0; m < 4; ++m) for (int n = 0; n < 2; ++n) for (int k = 0; k < 2; ++k) \
;       acc[ai][bj][m][n] = __builtin_amdgcn_mfma_f32_16x16x32_bf16(Bt_[n][k], At_[m][k], acc[ai][bj][m][n], 0, 0, 0); \
;     __builtin_amdgcn_s_setprio(0); } while (0)
; #define WAIT_V(n) asm volatile("s_waitcnt vmcnt(" #n ")" ::: "memory")
; #define WAIT_L(n) asm volatile("s_waitcnt lgkmcnt(" #n ")" ::: "memory")
; #define BAR __builtin_amdgcn_s_barrier()
;     ...
;   { LDB(B0, 0, 0); LDA(At, 0, 0); STAGE_A(SA(1, 1), brow + HALF, nt - 1);
;     BAR; WAIT_L(0); MMA(0, 0, At, B0); BAR;
;     LDB(B1, 0, 1); BAR; WAIT_L(0); MMA(0, 1, At, B1); BAR;
;     LDA(At, 0, 1); WAIT_V(4); BAR; WAIT_L(0); MMA(1, 0, At, B0); MMA(1, 1, At, B1); BAR; }
;   { LDB(B0, 1, 0); LDA(At, 1, 0); WAIT_V(2); BAR; WAIT_L(0); MMA(0, 0, At, B0); BAR;
;     LDB(B1, 1, 1); WAIT_V(0); BAR; WAIT_L(0); MMA(0, 1, At, B1); BAR;
;     LDA(At, 1, 1); BAR; WAIT_L(0); MMA(1, 0, At, B0); MMA(1, 1, At, B1); BAR; }
	s_waitcnt lgkmcnt(0)
	s_setprio 1
	s_waitcnt lgkmcnt(0)
	v_mfma_f32_16x16x32_bf16 v[60:63], v[132:135], v[172:175], v[60:63]
	v_mfma_f32_16x16x32_bf16 v[56:59], v[164:167], v[172:175], v[56:59]
	v_mfma_f32_16x16x32_bf16 v[52:55], v[132:135], v[182:185], v[52:55]
	v_mfma_f32_16x16x32_bf16 v[48:51], v[164:167], v[182:185], v[48:51]
	v_mfma_f32_16x16x32_bf16 v[44:47], v[132:135], v[190:193], v[44:47]
	v_mfma_f32_16x16x32_bf16 v[40:43], v[164:167], v[190:193], v[40:43]
	v_mfma_f32_16x16x32_bf16 v[36:39], v[132:135], v[198:201], v[36:39]
	v_mfma_f32_16x16x32_bf16 v[32:35], v[164:167], v[198:201], v[32:35]
	v_mfma_f32_16x16x32_bf16 v[60:63], v[160:163], v[176:179], v[60:63]
	v_mfma_f32_16x16x32_bf16 v[56:59], v[168:171], v[176:179], v[56:59]
	v_mfma_f32_16x16x32_bf16 v[52:55], v[160:163], v[186:189], v[52:55]
	v_mfma_f32_16x16x32_bf16 v[48:51], v[168:171], v[186:189], v[48:51]
	v_mfma_f32_16x16x32_bf16 v[44:47], v[160:163], v[194:197], v[44:47]
	v_mfma_f32_16x16x32_bf16 v[40:43], v[168:171], v[194:197], v[40:43]
	v_mfma_f32_16x16x32_bf16 v[36:39], v[160:163], v[202:205], v[36:39]
	v_mfma_f32_16x16x32_bf16 v[32:35], v[168:171], v[202:205], v[32:35]
	s_setprio 0
	s_setprio 1
	v_mfma_f32_16x16x32_bf16 v[28:31], v[206:209], v[172:175], v[28:31]
	v_mfma_f32_16x16x32_bf16 v[24:27], v[214:217], v[172:175], v[24:27]
	v_mfma_f32_16x16x32_bf16 v[20:23], v[206:209], v[182:185], v[20:23]
	v_mfma_f32_16x16x32_bf16 v[16:19], v[214:217], v[182:185], v[16:19]
	v_mfma_f32_16x16x32_bf16 v[12:15], v[206:209], v[190:193], v[12:15]
	v_mfma_f32_16x16x32_bf16 v[8:11], v[214:217], v[190:193], v[8:11]
	v_mfma_f32_16x16x32_bf16 v[4:7], v[206:209], v[198:201], v[4:7]
	v_mfma_f32_16x16x32_bf16 v[0:3], v[214:217], v[198:201], v[0:3]
	v_mfma_f32_16x16x32_bf16 v[28:31], v[210:213], v[176:179], v[28:31]
	v_mfma_f32_16x16x32_bf16 v[24:27], v[218:221], v[176:179], v[24:27]
	v_mfma_f32_16x16x32_bf16 v[20:23], v[210:213], v[186:189], v[20:23]
	v_mfma_f32_16x16x32_bf16 v[16:19], v[218:221], v[186:189], v[16:19]
	v_mfma_f32_16x16x32_bf16 v[12:15], v[210:213], v[194:197], v[12:15]
	v_mfma_f32_16x16x32_bf16 v[8:11], v[218:221], v[194:197], v[8:11]
	s_setprio 2
	s_barrier
	v_mfma_f32_16x16x32_bf16 v[4:7], v[210:213], v[202:205], v[4:7]
	v_mfma_f32_16x16x32_bf16 v[0:3], v[218:221], v[202:205], v[0:3]
	s_setprio 0
	ds_read_b128 v[132:135], v149 offset:32768
	ds_read_b128 v[158:161], v149 offset:33792
	ds_read_b128 v[162:165], v149 offset:34816
	ds_read_b128 v[166:169], v149 offset:35840
	ds_read_b128 v[170:173], v148 offset:32768
	ds_read_b128 v[174:177], v148 offset:33792
	ds_read_b128 v[182:185], v148 offset:34816
	ds_read_b128 v[186:189], v148 offset:35840
	ds_read_b128 v[190:193], v148 offset:36864
	ds_read_b128 v[194:197], v148 offset:37888
	ds_read_b128 v[198:201], v148 offset:38912
	ds_read_b128 v[202:205], v148 offset:39936
	s_waitcnt vmcnt(2)
	s_barrier
	s_waitcnt lgkmcnt(0)
	s_setprio 1
	s_waitcnt lgkmcnt(0)
	v_mfma_f32_16x16x32_bf16 v[124:127], v[132:135], v[170:173], v[124:127]
	v_mfma_f32_16x16x32_bf16 v[120:123], v[162:165], v[170:173], v[120:123]
	v_mfma_f32_16x16x32_bf16 v[116:119], v[132:135], v[182:185], v[116:119]
	v_mfma_f32_16x16x32_bf16 v[112:115], v[162:165], v[182:185], v[112:115]
	v_mfma_f32_16x16x32_bf16 v[108:111], v[132:135], v[190:193], v[108:111]
	v_mfma_f32_16x16x32_bf16 v[104:107], v[162:165], v[190:193], v[104:107]
	v_mfma_f32_16x16x32_bf16 v[100:103], v[132:135], v[198:201], v[100:103]
	v_mfma_f32_16x16x32_bf16 v[96:99], v[162:165], v[198:201], v[96:99]
	v_mfma_f32_16x16x32_bf16 v[124:127], v[158:161], v[174:177], v[124:127]
	v_mfma_f32_16x16x32_bf16 v[120:123], v[166:169], v[174:177], v[120:123]
	v_mfma_f32_16x16x32_bf16 v[116:119], v[158:161], v[186:189], v[116:119]
	v_mfma_f32_16x16x32_bf16 v[112:115], v[166:169], v[186:189], v[112:115]
	v_mfma_f32_16x16x32_bf16 v[108:111], v[158:161], v[194:197], v[108:111]
	v_mfma_f32_16x16x32_bf16 v[104:107], v[166:169], v[194:197], v[104:107]
	s_setprio 2
	s_barrier
	v_mfma_f32_16x16x32_bf16 v[100:103], v[158:161], v[202:205], v[100:103]
	v_mfma_f32_16x16x32_bf16 v[96:99], v[166:169], v[202:205], v[96:99]
	s_setprio 0
	ds_read_b128 v[206:209], v149 offset:49152
	ds_read_b128 v[210:213], v149 offset:50176
	ds_read_b128 v[214:217], v149 offset:51200
	ds_read_b128 v[218:221], v149 offset:52224
	s_waitcnt vmcnt(0)
	s_barrier
	s_waitcnt lgkmcnt(0)
	s_setprio 1
	s_waitcnt lgkmcnt(0)
	v_mfma_f32_16x16x32_bf16 v[92:95], v[206:209], v[170:173], v[92:95]
	v_mfma_f32_16x16x32_bf16 v[88:91], v[214:217], v[170:173], v[88:91]
	v_mfma_f32_16x16x32_bf16 v[84:87], v[206:209], v[182:185], v[84:87]
	v_mfma_f32_16x16x32_bf16 v[80:83], v[214:217], v[182:185], v[80:83]
	v_mfma_f32_16x16x32_bf16 v[76:79], v[206:209], v[190:193], v[76:79]
	v_mfma_f32_16x16x32_bf16 v[72:75], v[214:217], v[190:193], v[72:75]
	v_mfma_f32_16x16x32_bf16 v[68:71], v[206:209], v[198:201], v[68:71]
	v_mfma_f32_16x16x32_bf16 v[64:67], v[214:217], v[198:201], v[64:67]
	v_mfma_f32_16x16x32_bf16 v[92:95], v[210:213], v[174:177], v[92:95]
	v_mfma_f32_16x16x32_bf16 v[88:91], v[218:221], v[174:177], v[88:91]
	v_mfma_f32_16x16x32_bf16 v[84:87], v[210:213], v[186:189], v[84:87]
	v_mfma_f32_16x16x32_bf16 v[80:83], v[218:221], v[186:189], v[80:83]
	v_mfma_f32_16x16x32_bf16 v[76:79], v[210:213], v[194:197], v[76:79]
	v_mfma_f32_16x16x32_bf16 v[72:75], v[218:221], v[194:197], v[72:75]
	s_setprio 2
	s_barrier
; #define STAGE_A(P, br, kt) do { const char* _base = (const char*)(((kt) < G.ksplit ? G.A1 : A2m) + (long)(br) * G.lda + (long)(kt) * BK); \
;     __builtin_amdgcn_global_load_lds((const unsigned*)(_base + aoff0), (unsigned*)((char*)(P) + sb0), 16, 0, 0); \
;     __builtin_amdgcn_global_load_lds((const unsigned*)(_base + aoff1), (unsigned*)((char*)(P) + sb1), 16, 0, 0); } while (0)
; #define STAGE_B(P, br, kt) do { const char* _base = (const char*)(G.Bt + (long)(br) * G.ldb + (long)(kt) * BK); \
;     __builtin_amdgcn_global_load_lds((const unsigned*)(_base + boff0), (unsigned*)((char*)(P) + sb0), 16, 0, 0); \
;     __builtin_amdgcn_global_load_lds((const unsigned*)(_base + boff1), (unsigned*)((char*)(P) + sb1), 16, 0, 0); } while (0)
; #define LDA(dst, b, h) for (int m = 0; m < 4; ++m) for (int k = 0; k < 2; ++k) \
;     dst[m][k] = *reinterpret_cast<const bf16x8*>(a_rd + ((b) * 2 + (h)) * (HT * 2) + m * 2048 + k * 1024)
; #define LDB(dst, b, h) for (int n = 0; n < 2; ++n) for (int k = 0; k < 2; ++k) \
;     dst[n][k] = *reinterpret_cast<const bf16x8*>(b_rd + ((b) * 2 + (h)) * (HT * 2) + n * 2048 + k * 1024)
; #define MMA(ai, bj, At_, Bt_) do { __builtin_amdgcn_s_setprio(1); \
;     for (int m = 0; m < 4; ++m) for (int n = 0; n < 2; ++n) for (int k = 0; k < 2; ++k) \
;       acc[ai][bj][m][n] = __builtin_amdgcn_mfma_f32_16x16x32_bf16(Bt_[n][k], At_[m][k], acc[ai][bj][m][n], 0, 0, 0); \
;     __builtin_amdgcn_s_setprio(0); } while (0)
; #define WAIT_V(n) asm volatile("s_waitcnt vmcnt(" #n ")" ::: "memory")
; #define WAIT_L(n) asm volatile("s_waitcnt lgkmcnt(" #n ")" ::: "memory")
; #define BAR __builtin_amdgcn_s_barrier()
;     ...
;   { LDB(B0, 1, 0); LDA(At, 1, 0); WAIT_V(2); BAR; WAIT_L(0); MMA(0, 0, At, B0); BAR;
;     LDB(B1, 1, 1); WAIT_V(0); BAR; WAIT_L(0); MMA(0, 1, At, B1); BAR;
;     LDA(At, 1, 1); BAR; WAIT_L(0); MMA(1, 0, At, B0); MMA(1, 1, At, B1); BAR; }
;   if (wr == 0) BAR;
;   if (EPI != EPI_RESID && has_next) {
;     STAGE_B(SB(0, 0), nbcol, 0); STAGE_A(SA(0, 0), nbrow, 0);
;     STAGE_B(SB(0, 1), nbcol + HALF, 0); STAGE_A(SA(0, 1), nbrow + HALF, 0);
;   }
	v_mfma_f32_16x16x32_bf16 v[68:71], v[210:213], v[202:205], v[68:71]
	v_mfma_f32_16x16x32_bf16 v[64:67], v[218:221], v[202:205], v[64:67]
	s_setprio 0
	ds_read_b128 v[170:173], v148 offset:49152
	ds_read_b128 v[174:177], v148 offset:50176
	ds_read_b128 v[182:185], v148 offset:51200
	ds_read_b128 v[186:189], v148 offset:52224
	ds_read_b128 v[190:193], v148 offset:53248
	ds_read_b128 v[194:197], v148 offset:54272
	ds_read_b128 v[198:201], v148 offset:55296
	ds_read_b128 v[202:205], v148 offset:56320
	s_barrier
	s_waitcnt lgkmcnt(0)
	s_setprio 1
	s_waitcnt lgkmcnt(0)
	v_mfma_f32_16x16x32_bf16 v[60:63], v[132:135], v[170:173], v[60:63]
	v_mfma_f32_16x16x32_bf16 v[56:59], v[162:165], v[170:173], v[56:59]
	v_mfma_f32_16x16x32_bf16 v[52:55], v[132:135], v[182:185], v[52:55]
	v_mfma_f32_16x16x32_bf16 v[48:51], v[162:165], v[182:185], v[48:51]
	v_mfma_f32_16x16x32_bf16 v[44:47], v[132:135], v[190:193], v[44:47]
	v_mfma_f32_16x16x32_bf16 v[40:43], v[162:165], v[190:193], v[40:43]
	v_mfma_f32_16x16x32_bf16 v[36:39], v[132:135], v[198:201], v[36:39]
	v_mfma_f32_16x16x32_bf16 v[32:35], v[162:165], v[198:201], v[32:35]
	v_mfma_f32_16x16x32_bf16 v[60:63], v[158:161], v[174:177], v[60:63]
	v_mfma_f32_16x16x32_bf16 v[56:59], v[166:169], v[174:177], v[56:59]
	v_mfma_f32_16x16x32_bf16 v[52:55], v[158:161], v[186:189], v[52:55]
	v_mfma_f32_16x16x32_bf16 v[48:51], v[166:169], v[186:189], v[48:51]
	v_mfma_f32_16x16x32_bf16 v[44:47], v[158:161], v[194:197], v[44:47]
	v_mfma_f32_16x16x32_bf16 v[40:43], v[166:169], v[194:197], v[40:43]
	v_mfma_f32_16x16x32_bf16 v[36:39], v[158:161], v[202:205], v[36:39]
	v_mfma_f32_16x16x32_bf16 v[32:35], v[166:169], v[202:205], v[32:35]
	s_setprio 0
	s_setprio 1
	v_mfma_f32_16x16x32_bf16 v[28:31], v[206:209], v[170:173], v[28:31]
	v_mfma_f32_16x16x32_bf16 v[24:27], v[214:217], v[170:173], v[24:27]
	v_mfma_f32_16x16x32_bf16 v[20:23], v[206:209], v[182:185], v[20:23]
	v_mfma_f32_16x16x32_bf16 v[16:19], v[214:217], v[182:185], v[16:19]
	v_mfma_f32_16x16x32_bf16 v[12:15], v[206:209], v[190:193], v[12:15]
	v_mfma_f32_16x16x32_bf16 v[8:11], v[214:217], v[190:193], v[8:11]
	v_mfma_f32_16x16x32_bf16 v[4:7], v[206:209], v[198:201], v[4:7]
	v_mfma_f32_16x16x32_bf16 v[0:3], v[214:217], v[198:201], v[0:3]
	v_mfma_f32_16x16x32_bf16 v[28:31], v[210:213], v[174:177], v[28:31]
	v_mfma_f32_16x16x32_bf16 v[24:27], v[218:221], v[174:177], v[24:27]
	v_mfma_f32_16x16x32_bf16 v[20:23], v[210:213], v[186:189], v[20:23]
	v_mfma_f32_16x16x32_bf16 v[16:19], v[218:221], v[186:189], v[16:19]
	v_readfirstlane_b32 s26, v224
	v_mfma_f32_16x16x32_bf16 v[12:15], v[210:213], v[194:197], v[12:15]
	v_mfma_f32_16x16x32_bf16 v[8:11], v[218:221], v[194:197], v[8:11]
	s_setprio 2
	s_bitcmp0_b32 s26, 8
	s_cbranch_scc0 .Lmy_t6skip_2
	s_barrier
.Lmy_t6skip_2:
	v_mfma_f32_16x16x32_bf16 v[4:7], v[210:213], v[202:205], v[4:7]
	v_mfma_f32_16x16x32_bf16 v[0:3], v[218:221], v[202:205], v[0:3]
	s_setprio 0
	s_andn2_b64 vcc, exec, s[6:7]
	s_cbranch_vccnz .LBB0_1870
	s_lshl_b64 s[6:7], s[8:9], 1
	s_add_u32 s6, s39, s6
	s_addc_u32 s7, s40, s7
	v_readfirstlane_b32 s8, v155
	v_lshl_add_u64 v[132:133], s[6:7], 0, v[180:181]
	s_mov_b32 m0, s8
	v_readfirstlane_b32 s8, v156
	s_mul_i32 s26, s28, 0x1080
	global_load_lds_dwordx4 v[132:133], off
	s_mov_b32 m0, s8
	s_mul_hi_i32 s9, s28, 0x1080
	s_add_u32 s8, s37, s26
	v_lshl_add_u64 v[132:133], s[6:7], 0, v[128:129]
	s_addc_u32 s9, s38, s9
	v_readfirstlane_b32 s27, v147
	global_load_lds_dwordx4 v[132:133], off
	v_lshl_add_u64 v[132:133], s[8:9], 0, v[180:181]
	s_mov_b32 m0, s27
	s_add_u32 s6, s6, 0x84000
	global_load_lds_dwordx4 v[132:133], off
	v_lshl_add_u64 v[132:133], s[8:9], 0, v[128:129]
	v_readfirstlane_b32 s8, v146
	s_mov_b32 m0, s8
	s_addc_u32 s7, s7, 0
	v_readfirstlane_b32 s8, v141
	global_load_lds_dwordx4 v[132:133], off
	v_lshl_add_u64 v[132:133], s[6:7], 0, v[180:181]
	s_mov_b32 m0, s8
	s_add_i32 s26, s26, 0x84000
	global_load_lds_dwordx4 v[132:133], off
	v_lshl_add_u64 v[132:133], s[6:7], 0, v[128:129]
	v_readfirstlane_b32 s6, v157
	s_mov_b32 m0, s6
	s_add_i32 s6, s28, 0x80
	s_mul_hi_i32 s7, s6, 0x1080
	s_add_u32 s6, s37, s26
	s_addc_u32 s7, s38, s7
	v_readfirstlane_b32 s8, v140
	global_load_lds_dwordx4 v[132:133], off
	v_lshl_add_u64 v[132:133], s[6:7], 0, v[180:181]
	s_mov_b32 m0, s8
	v_lshl_add_u64 v[128:129], s[6:7], 0, v[128:129]
	v_readfirstlane_b32 s6, v138
	global_load_lds_dwordx4 v[132:133], off
	s_mov_b32 m0, s6
	s_nop 0
	global_load_lds_dwordx4 v[128:129], off
